# diff attention: exp/cvt/row-sum VALU interleaved into PV MFMA gaps (same arithmetic order), P3 in free regs
# speedup vs baseline: 1.0237x; 1.0161x over previous
.LBB0_801:
	s_add_u32 s10, s10, 0x60000
	s_addc_u32 s11, s11, 0
	s_add_i32 s29, s29, 1
	s_cmp_lg_u32 s10, 0x1800000
	s_cbranch_scc0 .LBB0_811

.LBB0_808:
	v_exp_f32_e32 v98, v98
	v_exp_f32_e32 v99, v99
	v_exp_f32_e32 v100, v100
	v_exp_f32_e32 v101, v101
	v_exp_f32_e32 v102, v102
	v_exp_f32_e32 v103, v103
	v_exp_f32_e32 v104, v104
	v_exp_f32_e32 v105, v105
	v_cvt_pk_bf16_f32 v214, v98, v99
	v_cvt_pk_bf16_f32 v215, v100, v101
	v_cvt_pk_bf16_f32 v216, v102, v103
	v_cvt_pk_bf16_f32 v217, v104, v105
	ds_read_b64_tr_b16 v[226:227], v213 offset:14336
	ds_read_b64_tr_b16 v[230:231], v213 offset:14400
	ds_read_b64_tr_b16 v[234:235], v213 offset:14464
	ds_read_b64_tr_b16 v[238:239], v213 offset:14528
	ds_read_b64_tr_b16 v[228:229], v213 offset:16896
	ds_read_b64_tr_b16 v[232:233], v213 offset:16960
	ds_read_b64_tr_b16 v[236:237], v213 offset:17024
	ds_read_b64_tr_b16 v[240:241], v213 offset:17088
	s_setprio 1
	s_waitcnt lgkmcnt(11)
	v_mfma_f32_32x32x16_bf16 v[50:65], v[154:157], v[214:217], v[50:65]
	v_exp_f32_e32 v106, v106
	v_exp_f32_e32 v107, v107
	s_waitcnt lgkmcnt(10)
	v_mfma_f32_32x32x16_bf16 v[34:49], v[150:153], v[214:217], v[34:49]
	v_exp_f32_e32 v108, v108
	v_exp_f32_e32 v109, v109
	v_cvt_pk_bf16_f32 v218, v106, v107
	s_waitcnt lgkmcnt(9)
	v_mfma_f32_32x32x16_bf16 v[18:33], v[146:149], v[214:217], v[18:33]
	v_exp_f32_e32 v110, v110
	v_exp_f32_e32 v111, v111
	v_cvt_pk_bf16_f32 v219, v108, v109
	s_waitcnt lgkmcnt(8)
	v_mfma_f32_32x32x16_bf16 v[2:17], v[142:145], v[214:217], v[2:17]
	v_exp_f32_e32 v112, v112
	v_exp_f32_e32 v113, v113
	v_cvt_pk_bf16_f32 v220, v110, v111
	v_cvt_pk_bf16_f32 v221, v112, v113
	s_setprio 0
	ds_read_b64_tr_b16 v[142:143], v213 offset:19456
	ds_read_b64_tr_b16 v[146:147], v213 offset:19520
	ds_read_b64_tr_b16 v[150:151], v213 offset:19584
	ds_read_b64_tr_b16 v[154:155], v213 offset:19648
	ds_read_b64_tr_b16 v[144:145], v213 offset:22016
	ds_read_b64_tr_b16 v[148:149], v213 offset:22080
	ds_read_b64_tr_b16 v[152:153], v213 offset:22144
	ds_read_b64_tr_b16 v[156:157], v213 offset:22208
	s_setprio 1
	s_waitcnt lgkmcnt(11)
	v_mfma_f32_32x32x16_bf16 v[50:65], v[226:229], v[218:221], v[50:65]
	v_exp_f32_e32 v82, v82
	v_exp_f32_e32 v83, v83
	v_add_f32_e32 v98, v100, v98
	v_add_f32_e32 v99, v99, v101
	s_waitcnt lgkmcnt(10)
	v_mfma_f32_32x32x16_bf16 v[34:49], v[230:233], v[218:221], v[34:49]
	v_exp_f32_e32 v84, v84
	v_exp_f32_e32 v85, v85
	v_cvt_pk_bf16_f32 v222, v82, v83
	v_add_f32_e32 v98, v98, v102
	s_waitcnt lgkmcnt(9)
	v_mfma_f32_32x32x16_bf16 v[18:33], v[234:237], v[218:221], v[18:33]
	v_exp_f32_e32 v86, v86
	v_exp_f32_e32 v87, v87
	v_cvt_pk_bf16_f32 v223, v84, v85
	v_add_f32_e32 v99, v103, v99
	s_waitcnt lgkmcnt(8)
	v_mfma_f32_32x32x16_bf16 v[2:17], v[238:241], v[218:221], v[2:17]
	v_exp_f32_e32 v88, v88
	v_exp_f32_e32 v89, v89
	v_cvt_pk_bf16_f32 v224, v86, v87
	v_cvt_pk_bf16_f32 v225, v88, v89
	s_setprio 0
	ds_read_b64_tr_b16 v[214:215], v213 offset:24576
	ds_read_b64_tr_b16 v[218:219], v213 offset:24640
	ds_read_b64_tr_b16 v[226:227], v213 offset:24704
	ds_read_b64_tr_b16 v[230:231], v213 offset:24768
	ds_read_b64_tr_b16 v[216:217], v213 offset:27136
	ds_read_b64_tr_b16 v[220:221], v213 offset:27200
	ds_read_b64_tr_b16 v[228:229], v213 offset:27264
	ds_read_b64_tr_b16 v[232:233], v213 offset:27328
	s_setprio 1
	s_waitcnt lgkmcnt(11)
	v_mfma_f32_32x32x16_bf16 v[50:65], v[142:145], v[222:225], v[50:65]
	v_exp_f32_e32 v90, v90
	v_exp_f32_e32 v91, v91
	v_add_f32_e32 v98, v104, v98
	v_add_f32_e32 v99, v105, v99
	s_waitcnt lgkmcnt(10)
	v_mfma_f32_32x32x16_bf16 v[34:49], v[146:149], v[222:225], v[34:49]
	v_exp_f32_e32 v92, v92
	v_exp_f32_e32 v93, v93
	v_cvt_pk_bf16_f32 v242, v90, v91
	v_add_f32_e32 v98, v106, v98
	s_waitcnt lgkmcnt(9)
	v_mfma_f32_32x32x16_bf16 v[18:33], v[150:153], v[222:225], v[18:33]
	v_exp_f32_e32 v94, v94
	v_exp_f32_e32 v95, v95
	v_cvt_pk_bf16_f32 v243, v92, v93
	v_add_f32_e32 v99, v107, v99
	s_waitcnt lgkmcnt(8)
	v_mfma_f32_32x32x16_bf16 v[2:17], v[154:157], v[222:225], v[2:17]
	v_exp_f32_e32 v96, v96
	v_exp_f32_e32 v97, v97
	v_cvt_pk_bf16_f32 v244, v94, v95
	v_cvt_pk_bf16_f32 v245, v96, v97
	s_nop 1
	s_waitcnt lgkmcnt(3)
	v_mfma_f32_32x32x16_bf16 v[50:65], v[214:217], v[242:245], v[50:65]
	v_add_f32_e32 v98, v108, v98
	v_add_f32_e32 v99, v109, v99
	v_add_f32_e32 v98, v110, v98
	v_add_f32_e32 v99, v111, v99
	v_add_f32_e32 v98, v112, v98
	v_add_f32_e32 v99, v113, v99
	s_waitcnt lgkmcnt(2)
	v_mfma_f32_32x32x16_bf16 v[34:49], v[218:221], v[242:245], v[34:49]
	v_add_f32_e32 v82, v82, v98
	v_add_f32_e32 v83, v83, v99
	v_add_f32_e32 v82, v84, v82
	v_add_f32_e32 v83, v85, v83
	v_add_f32_e32 v82, v86, v82
	v_add_f32_e32 v83, v87, v83
	s_waitcnt lgkmcnt(1)
	v_mfma_f32_32x32x16_bf16 v[18:33], v[226:229], v[242:245], v[18:33]
	v_add_f32_e32 v82, v88, v82
	v_add_f32_e32 v83, v89, v83
	v_add_f32_e32 v82, v90, v82
	v_add_f32_e32 v83, v91, v83
	v_add_f32_e32 v82, v92, v82
	v_add_f32_e32 v83, v93, v83
	s_waitcnt lgkmcnt(0)
	v_mfma_f32_32x32x16_bf16 v[2:17], v[230:233], v[242:245], v[2:17]
	s_setprio 0
	v_add_f32_e32 v82, v94, v82
	v_add_f32_e32 v83, v95, v83
	v_add_f32_e32 v82, v96, v82
	v_add_f32_e32 v83, v97, v83
	v_add_f32_e32 v82, v82, v83
	v_add_f32_e32 v0, v0, v82
	s_cmp_eq_u32 s10, 0x17a0000
	s_cbranch_scc1 .LBB0_801
	s_xor_b32 s12, s30, 1
	s_mulk_i32 s12, 0x7400
	s_add_i32 s12, s12, 0
	v_add3_u32 v142, s12, v206, v183
	s_waitcnt vmcnt(2)
	ds_write_b128 v142, v[130:133]
	v_add3_u32 v142, s12, v205, v207
	s_cmp_gt_u32 s29, 61
	s_waitcnt vmcnt(1)
	ds_write_b128 v142, v[134:137] offset:9216
	s_waitcnt vmcnt(0)
	ds_write_b128 v142, v[138:141] offset:19456
	s_cbranch_scc1 .LBB0_801
	v_lshl_add_u64 v[130:131], v[188:189], 0, s[10:11]
	v_lshl_add_u64 v[134:135], v[190:191], 0, s[10:11]
	v_lshl_add_u64 v[138:139], v[192:193], 0, s[10:11]
	global_load_dwordx4 v[130:133], v[130:131], off
	s_nop 0
	global_load_dwordx4 v[134:137], v[134:135], off
	s_nop 0
	global_load_dwordx4 v[138:141], v[138:139], off
	s_branch .LBB0_801
